# mixer dynamic queue: ctx SWA attention pairs dispatched before ctx NAT pairs (order of the last two classes swapped)
# speedup vs baseline: 1.0069x; 1.0023x over previous
.LBB0_230:
	s_cmpk_gt_i32 s4, 0x27f
	s_mov_b64 s[0:1], -1
	s_cbranch_scc1 .LBB0_229
	s_lshl_b32 s82, s4, 1
	s_add_i32 s82, s82, s77
	s_cmpk_lt_u32 s82, 0x300
	s_cbranch_scc1 .Lq_noswap
	s_xor_b32 s82, s82, 0x700
.Lq_noswap:
	s_cmpk_gt_i32 s82, 0x7f
	s_cbranch_scc0 .LBB0_429
	s_cmpk_gt_u32 s82, 0x27f
	s_cbranch_scc0 .LBB0_411
	s_cmpk_gt_u32 s82, 0x2bf
	s_cbranch_scc0 .LBB0_338
	s_cmpk_gt_u32 s82, 0x2ff
	s_cbranch_scc0 .LBB0_248
	s_cmpk_gt_u32 s82, 0x3ff
	s_cbranch_scc0 .LBB0_241
	s_lshl_b32 s0, s82, 5
	s_add_i32 s0, s0, 0x7fff8000
	v_mov_b32 v0, 0
	s_and_b32 s6, s0, 0x7fffff00
	v_add_u32_sdwa v8, v0, v160 dst_sel:DWORD dst_unused:UNUSED_PAD src0_sel:DWORD src1_sel:BYTE_0
	v_readlane_b32 s0, v254, 59
	v_and_b32_e32 v9, 31, v8
	s_or_b32 s0, s0, s6
	v_or_b32_e32 v1, s0, v9
	s_lshl_b32 s0, s82, 4
	s_bfe_u32 s5, s82, 0x20001
	s_and_b32 s7, s0, 64
	v_readlane_b32 s0, v254, 60
	s_or_b32 s0, s5, s0
	s_ashr_i32 s1, s0, 31
	v_readlane_b32 s12, v254, 14
	v_ashrrev_i32_e32 v0, 1, v8
	s_lshl_b32 s4, s5, 6
	s_or_b32 s8, s7, 0xd80
	s_lshl_b64 s[0:1], s[0:1], 2
	v_readlane_b32 s20, v254, 22
	v_and_b32_e32 v0, 0xffffffe0, v0
	v_readlane_b32 s21, v254, 23
	s_add_u32 s0, s20, s0
	v_add_u32_e32 v96, v1, v0
	s_addc_u32 s1, s21, s1
	v_mov_b64_e32 v[0:1], s[62:63]
	v_bfe_u32 v98, v8, 5, 1
	global_load_dword v99, v129, s[0:1]
	v_mad_i64_i32 v[2:3], s[0:1], v96, s87, v[0:1]
	s_lshl_b32 s92, s5, 7
	v_lshl_add_u64 v[2:3], v[2:3], 0, s[92:93]
	v_lshlrev_b32_e32 v128, 4, v98
	v_lshl_add_u64 v[2:3], v[2:3], 0, v[128:129]
	s_mov_b64 s[0:1], 0x1900
	v_ashrrev_i32_e32 v11, 2, v8
	v_lshl_add_u64 v[4:5], v[2:3], 0, s[0:1]
	s_movk_i32 s0, 0x1000
	s_or_b32 s7, s7, 0xe00
	v_add_u32_e32 v13, s6, v11
	v_add_co_u32_e32 v2, vcc, s0, v2
	v_mad_i64_i32 v[0:1], s[0:1], v13, s87, v[0:1]
	s_lshl_b32 s92, s7, 1
	v_and_b32_e32 v12, 3, v8
	v_lshl_add_u64 v[6:7], v[0:1], 0, s[92:93]
	s_lshl_b32 s92, s8, 1
	v_lshlrev_b32_e32 v128, 5, v12
	v_lshl_add_u64 v[0:1], v[0:1], 0, s[92:93]
	v_lshl_add_u64 v[0:1], v[0:1], 0, v[128:129]
	v_addc_co_u32_e32 v3, vcc, 0, v3, vcc
	global_load_dwordx4 v[64:67], v[4:5], off offset:32
	global_load_dwordx4 v[68:71], v[4:5], off offset:64
	v_lshl_add_u64 v[6:7], v[6:7], 0, v[128:129]
	global_load_dwordx4 v[40:43], v[0:1], off offset:16
	global_load_dwordx4 v[44:47], v[0:1], off
	s_waitcnt lgkmcnt(0)
	global_load_dwordx4 v[32:35], v[6:7], off offset:16
	global_load_dwordx4 v[36:39], v[6:7], off
	global_load_dwordx4 v[72:75], v[2:3], off offset:2304
	global_load_dwordx4 v[76:79], v[4:5], off offset:96
	v_lshrrev_b32_e32 v1, 3, v8
	v_bfe_u32 v2, v8, 3, 3
	v_lshlrev_b32_e32 v4, 1, v12
	v_lshrrev_b32_e32 v10, 5, v8
	v_bitop3_b32 v1, v4, v1, 7 bitop3:0x78
	v_bitop3_b32 v2, v4, v2, 1 bitop3:0x36
	v_bfe_u32 v4, v8, 1, 3
	v_mul_u32_u24_e32 v8, 0x440, v12
	v_lshl_add_u32 v5, v9, 7, s78
	v_mul_u32_u24_e32 v7, 0x88, v9
	v_lshlrev_b32_e32 v8, 1, v8
	v_lshlrev_b32_e32 v9, 1, v11
	s_movk_i32 s0, 0xff82
	v_lshl_add_u32 v3, v11, 7, s78
	v_cmp_lt_i32_e32 vcc, v168, v167
	v_add3_u32 v101, s78, v8, v9
	v_mul_lo_u32 v9, v11, s0
	v_cndmask_b32_e32 v6, v165, v168, vcc
	v_add3_u32 v102, v3, v9, v8
	v_bitop3_b32 v8, v10, v4, 1 bitop3:0x6c
	v_bitop3_b32 v9, v98, v4, 2 bitop3:0x36
	v_bitop3_b32 v10, v98, v4, 4 bitop3:0x36
	v_bitop3_b32 v4, v98, v4, 6 bitop3:0x36
	v_lshlrev_b32_e32 v0, 4, v12
	v_lshlrev_b32_e32 v1, 4, v1
	v_lshlrev_b32_e32 v2, 4, v2
	v_lshlrev_b32_e32 v100, 2, v6
	v_lshl_add_u32 v6, v98, 3, s78
	v_lshlrev_b32_e32 v8, 4, v8
	v_lshlrev_b32_e32 v9, 4, v9
	v_lshlrev_b32_e32 v10, 4, v10
	v_lshlrev_b32_e32 v4, 4, v4
	v_mov_b32_e32 v105, 0
	v_ashrrev_i32_e32 v97, 31, v96
	s_mov_b32 s5, 0
	v_add_u32_e32 v103, 64, v13
	v_mov_b32_e32 v112, 0xf149f2ca
	s_lshl_b32 s92, s7, 1
	v_lshlrev_b32_e32 v128, 1, v0
	s_lshl_b32 s0, s8, 1
	v_add_u32_e32 v104, v3, v1
	v_add_u32_e32 v106, v3, v2
	v_add_u32_e32 v107, v5, v8
	v_add_u32_e32 v108, v5, v9
	v_add_u32_e32 v109, v5, v10
	v_add_u32_e32 v110, v5, v4
	v_add_u32_e32 v111, v6, v7
	v_mov_b32_e32 v16, 0
	v_mov_b32_e32 v17, v105
	v_mov_b32_e32 v18, v105
	v_mov_b32_e32 v19, v105
	v_mov_b32_e32 v20, v105
	v_mov_b32_e32 v21, v105
	v_mov_b32_e32 v22, v105
	v_mov_b32_e32 v23, v105
	v_mov_b32_e32 v24, v105
	v_mov_b32_e32 v25, v105
	v_mov_b32_e32 v26, v105
	v_mov_b32_e32 v27, v105
	v_mov_b32_e32 v28, v105
	v_mov_b32_e32 v29, v105
	v_mov_b32_e32 v30, v105
	v_mov_b32_e32 v31, v105
	v_mov_b32_e32 v0, 0
	v_mov_b32_e32 v1, v105
	v_mov_b32_e32 v2, v105
	v_mov_b32_e32 v3, v105
	v_mov_b32_e32 v4, v105
	v_mov_b32_e32 v5, v105
	v_mov_b32_e32 v6, v105
	v_mov_b32_e32 v7, v105
	v_mov_b32_e32 v8, v105
	v_mov_b32_e32 v9, v105
	v_mov_b32_e32 v10, v105
	s_waitcnt vmcnt(0)
	v_mov_b64_e32 v[94:95], v[42:43]
	v_mov_b64_e32 v[90:91], v[46:47]
	v_mov_b64_e32 v[86:87], v[34:35]
	v_mov_b64_e32 v[82:83], v[38:39]
	v_mov_b32_e32 v11, v105
	v_mov_b32_e32 v12, v105
	v_mov_b32_e32 v13, v105
	v_mov_b32_e32 v14, v105
	v_mov_b32_e32 v15, v105
	v_mov_b64_e32 v[88:89], v[44:45]
	v_mov_b64_e32 v[92:93], v[40:41]
	v_mov_b64_e32 v[80:81], v[36:37]
	v_mov_b64_e32 v[84:85], v[32:33]
	v_readlane_b32 s13, v254, 15
	v_readlane_b32 s14, v254, 16
	v_readlane_b32 s15, v254, 17
	v_readlane_b32 s16, v254, 18
	v_readlane_b32 s17, v254, 19
	v_readlane_b32 s18, v254, 20
	v_readlane_b32 s19, v254, 21
	v_readlane_b32 s22, v254, 24
	v_readlane_b32 s23, v254, 25
	v_readlane_b32 s24, v254, 26
	v_readlane_b32 s25, v254, 27
	v_readlane_b32 s26, v254, 28
	v_readlane_b32 s27, v254, 29
	s_cmpk_eq_i32 s5, 0xc0
	s_cbranch_scc1 .LBB0_239
	s_branch .LBB0_238
